# prep phase: x->bf16 row loop issues its 8 loads together (was load/wait/store x8 per row)
# baseline (speedup 1.0000x reference)
; __device__ __forceinline__ void st_bf4(bfraw* p, f32x4 v) { u32x2 o; o[0] = pack2(v[0], v[1]); o[1] = pack2(v[2], v[3]); *(u32x2*)p = o; }
; __device__ __forceinline__ void phase_prep(CPR P) {
;     ...
;     for (int row = blockIdx.x * 8 + wave; row < S; row += gridDim.x * 8) {
;         float s = 0.f;
; #pragma unroll
;         for (int i = 0; i < 8; ++i) {
;             const size_t o = (size_t)row * DM + i * 256 + lane * 4;
;             f32x4 v = __builtin_nontemporal_load((const f32x4*)(x + o));
;             s += (v[0] * v[0] + v[1] * v[1]) + (v[2] * v[2] + v[3] * v[3]);
;             st_bf4(xb + o, v);
;         }
;         s = wsum(s);
;         if (lane < 32) ssq[(size_t)row * 32 + lane] = lane == 0 ? s : 0.f;
;         if (lane == 0) ((float*)(P.ws + WS_RINV))[row] = rsqrtf(s * (1.0f / 2048.0f) + EPS);
;     }
.LBB0_367:
	v_ashrrev_i32_e32 v3, 31, v2
	v_lshlrev_b64 v[8:9], 11, v[2:3]
	v_or_b32_e32 v8, v8, v4
	s_mov_b64 s[98:99], 0x1000
	s_waitcnt lgkmcnt(0)
	v_lshl_add_u64 v[30:31], v[8:9], 2, s[10:11]
	v_lshl_add_u64 v[54:55], v[8:9], 1, s[12:13]
	v_lshl_add_u64 v[56:57], v[30:31], 0, s[98:99]
	global_load_dwordx4 v[18:21], v[30:31], off nt
	global_load_dwordx4 v[22:25], v[30:31], off offset:1024 nt
	global_load_dwordx4 v[26:29], v[30:31], off offset:2048 nt
	global_load_dwordx4 v[30:33], v[30:31], off offset:3072 nt
	global_load_dwordx4 v[36:39], v[56:57], off nt
	global_load_dwordx4 v[40:43], v[56:57], off offset:1024 nt
	global_load_dwordx4 v[44:47], v[56:57], off offset:2048 nt
	global_load_dwordx4 v[48:51], v[56:57], off offset:3072 nt
	s_waitcnt vmcnt(0)
	v_cvt_pk_bf16_f32 v62, v18, v19
	v_cvt_pk_bf16_f32 v63, v20, v21
	global_store_dwordx2 v[54:55], v[62:63], off
	v_cvt_pk_bf16_f32 v64, v22, v23
	v_cvt_pk_bf16_f32 v65, v24, v25
	global_store_dwordx2 v[54:55], v[64:65], off offset:512
	v_cvt_pk_bf16_f32 v62, v26, v27
	v_cvt_pk_bf16_f32 v63, v28, v29
	global_store_dwordx2 v[54:55], v[62:63], off offset:1024
	v_cvt_pk_bf16_f32 v64, v30, v31
	v_cvt_pk_bf16_f32 v65, v32, v33
	global_store_dwordx2 v[54:55], v[64:65], off offset:1536
	v_cvt_pk_bf16_f32 v62, v36, v37
	v_cvt_pk_bf16_f32 v63, v38, v39
	global_store_dwordx2 v[54:55], v[62:63], off offset:2048
	v_cvt_pk_bf16_f32 v64, v40, v41
	v_cvt_pk_bf16_f32 v65, v42, v43
	global_store_dwordx2 v[54:55], v[64:65], off offset:2560
	v_cvt_pk_bf16_f32 v62, v44, v45
	v_cvt_pk_bf16_f32 v63, v46, v47
	global_store_dwordx2 v[54:55], v[62:63], off offset:3072
	v_cvt_pk_bf16_f32 v64, v48, v49
	v_cvt_pk_bf16_f32 v65, v50, v51
	global_store_dwordx2 v[54:55], v[64:65], off offset:3584
	v_cmp_lt_i32_e64 s[6:7], v10, v5
	v_mul_f32_e32 v19, v19, v19
	v_mul_f32_e32 v21, v21, v21
	v_fmac_f32_e32 v19, v18, v18
	v_fmac_f32_e32 v21, v20, v20
	v_add_f32_e32 v18, v19, v21
	v_mul_f32_e32 v19, v23, v23
	v_mul_f32_e32 v20, v25, v25
	v_fmac_f32_e32 v19, v22, v22
	v_fmac_f32_e32 v20, v24, v24
	v_add_f32_e32 v19, v19, v20
	v_add_f32_e32 v18, v18, v19
	v_cndmask_b32_e64 v17, v1, v10, s[6:7]
	v_mul_f32_e32 v19, v27, v27
	v_mul_f32_e32 v20, v29, v29
	v_fmac_f32_e32 v19, v26, v26
	v_fmac_f32_e32 v20, v28, v28
	v_add_f32_e32 v19, v19, v20
	v_add_f32_e32 v18, v18, v19
	v_lshlrev_b32_e32 v17, 2, v17
	v_mul_f32_e32 v19, v31, v31
	v_mul_f32_e32 v20, v33, v33
	v_fmac_f32_e32 v19, v30, v30
	v_fmac_f32_e32 v20, v32, v32
	v_add_f32_e32 v19, v19, v20
	v_add_f32_e32 v18, v18, v19
	v_cmp_lt_i32_e64 s[6:7], v11, v5
	v_mul_f32_e32 v19, v37, v37
	v_mul_f32_e32 v20, v39, v39
	v_fmac_f32_e32 v19, v36, v36
	v_fmac_f32_e32 v20, v38, v38
	v_add_f32_e32 v19, v19, v20
	v_add_f32_e32 v18, v18, v19
	v_mul_f32_e32 v19, v41, v41
	v_mul_f32_e32 v20, v43, v43
	v_fmac_f32_e32 v19, v40, v40
	v_fmac_f32_e32 v20, v42, v42
	v_add_f32_e32 v19, v19, v20
	v_add_f32_e32 v18, v18, v19
	v_mul_f32_e32 v19, v45, v45
	v_mul_f32_e32 v20, v47, v47
	v_fmac_f32_e32 v19, v44, v44
	v_fmac_f32_e32 v20, v46, v46
	v_add_f32_e32 v19, v19, v20
	v_add_f32_e32 v18, v18, v19
	v_mul_f32_e32 v19, v49, v49
	v_mul_f32_e32 v20, v51, v51
	v_fmac_f32_e32 v19, v48, v48
	v_fmac_f32_e32 v20, v50, v50
	v_add_f32_e32 v19, v19, v20
	v_add_f32_e32 v18, v18, v19
	ds_bpermute_b32 v17, v17, v18
	v_cndmask_b32_e64 v19, v1, v11, s[6:7]
	v_lshlrev_b32_e32 v19, 2, v19
	v_cmp_lt_i32_e64 s[6:7], v12, v5
	s_waitcnt lgkmcnt(0)
	v_add_f32_e32 v17, v18, v17
	ds_bpermute_b32 v18, v19, v17
	v_cndmask_b32_e64 v19, v1, v12, s[6:7]
	v_lshlrev_b32_e32 v19, 2, v19
	v_cmp_lt_i32_e64 s[6:7], v13, v5
	s_waitcnt lgkmcnt(0)
	v_add_f32_e32 v17, v17, v18
	ds_bpermute_b32 v18, v19, v17
	v_cndmask_b32_e64 v19, v1, v13, s[6:7]
	v_lshlrev_b32_e32 v19, 2, v19
	v_cmp_lt_i32_e64 s[6:7], v14, v5
	s_waitcnt lgkmcnt(0)
	v_add_f32_e32 v17, v17, v18
	ds_bpermute_b32 v18, v19, v17
	v_cndmask_b32_e64 v19, v1, v14, s[6:7]
	v_lshlrev_b32_e32 v19, 2, v19
	v_cmp_lt_i32_e64 s[6:7], v15, v5
	s_waitcnt lgkmcnt(0)
	v_add_f32_e32 v17, v17, v18
	ds_bpermute_b32 v18, v19, v17
	v_cndmask_b32_e64 v19, v1, v15, s[6:7]
	s_waitcnt lgkmcnt(0)
	v_add_f32_e32 v17, v17, v18
	v_lshlrev_b32_e32 v18, 2, v19
	ds_bpermute_b32 v20, v18, v17
	s_waitcnt lgkmcnt(0)
	v_add_f32_e32 v8, v17, v20
	s_and_saveexec_b64 s[6:7], vcc
	s_cbranch_execz .LBB0_369
	v_lshlrev_b64 v[18:19], 7, v[2:3]
	v_lshl_add_u64 v[18:19], v[6:7], 0, v[18:19]
	v_cndmask_b32_e64 v9, 0, v8, s[4:5]
	global_store_dword v[18:19], v9, off
